# v48 + grid barrier: XCD leader no longer bumps the per-XCD generation word (nothing reads it since every workgroup polls the top-level generation word)
# baseline (speedup 1.0000x reference)
; __device__ __forceinline__ unsigned xb_add(unsigned* p, unsigned v) { return __hip_atomic_fetch_add(p, v, __ATOMIC_RELAXED, __HIP_MEMORY_SCOPE_AGENT); }
; __device__ __forceinline__ void xcd_barrier(const XcdBarrier& b, const int tid0) {
;     ...
;             __builtin_amdgcn_fence(__ATOMIC_ACQUIRE, "agent");
;             xb_add(&bar[XB_XGEN(b.x)], 1u);
;             asm volatile("s_waitcnt vmcnt(0)" ::: "memory");
.LBB0_4131:
	s_or_b64 exec, exec, s[4:5]
	v_mov_b32_e32 v0, 0x2000
	v_mov_b32_e32 v1, 1
	s_waitcnt vmcnt(0)
	buffer_inv sc1
	s_waitcnt vmcnt(0)

; __device__ __forceinline__ unsigned xb_add(unsigned* p, unsigned v) { return __hip_atomic_fetch_add(p, v, __ATOMIC_RELAXED, __HIP_MEMORY_SCOPE_AGENT); }
; __device__ __forceinline__ void xcd_barrier(const XcdBarrier& b, const int tid0) {
;     ...
;             __builtin_amdgcn_fence(__ATOMIC_ACQUIRE, "agent");
;             xb_add(&bar[XB_XGEN(b.x)], 1u);
;             asm volatile("s_waitcnt vmcnt(0)" ::: "memory");
.LBB0_4204:
	s_or_b64 exec, exec, s[4:5]
	v_mov_b32_e32 v0, 1
	v_mov_b32_e32 v1, 0x2000
	s_waitcnt vmcnt(0)
	buffer_inv sc1
	s_waitcnt vmcnt(0)
